# attention: permanent shuffle index, tile-b probabilities packed into spare registers so its row sums ride in the PV(b) block, half of tile-b exp moved under PV(b)
# speedup vs baseline: 1.1013x; 1.0095x over previous
.LBB0_111:
	v_and_b32_e32 v170, 63, v4
	v_lshlrev_b32_e32 v2, 3, v5
	s_and_b32 s12, s5, 0xffffe000
	v_lshlrev_b32_e32 v172, 2, v5
	v_lshrrev_b32_e32 v3, 2, v4
	v_lshlrev_b32_e32 v5, 1, v4
	v_lshlrev_b32_e32 v4, 3, v4
	v_or_b32_e32 v2, s2, v2
	v_and_or_b32 v3, v3, 3, v172
	v_and_b32_e32 v5, 32, v5
	v_and_b32_e32 v4, 24, v4
	v_add_u32_e32 v0, s12, v0
	v_mov_b32_e32 v14, v1
	v_mov_b32_e32 v15, v1
	s_lshl_b32 s3, s10, 1
	s_lshr_b32 s13, s8, 1
	v_mul_u32_u24_e32 v171, 0x110, v6
	v_mad_u32_u24 v178, v6, s26, 0
	v_add3_u32 v179, s16, v5, v4
	v_lshlrev_b32_e32 v180, 1, v2
	v_mul_u32_u24_e32 v181, 0x100, v3
	v_add_u32_e32 v179, v179, v181
	v_and_b32_e32 v181, 3, v3
	v_lshl_add_u32 v179, v181, 6, v179
	v_and_b32_e32 v195, 64, v220
	v_xor_b32_e32 v181, 32, v220
	v_add_u32_e32 v195, 64, v195
	v_cmp_lt_i32_e32 vcc, v181, v195
	s_nop 1
	v_cndmask_b32_e32 v181, v220, v181, vcc
	v_lshlrev_b32_e32 v181, 2, v181
	v_add_u32_e32 v164, 0x160, v0
	v_mov_b32_e32 v0, v1
	v_mov_b32_e32 v2, v1
	v_mov_b32_e32 v3, v1
	v_mov_b32_e32 v4, v1
	v_mov_b32_e32 v5, v1
	v_mov_b32_e32 v6, v1
	v_mov_b32_e32 v7, v1
	v_mov_b32_e32 v8, v1
	v_mov_b32_e32 v9, v1
	v_mov_b32_e32 v10, v1
	v_mov_b32_e32 v11, v1
	v_mov_b32_e32 v12, v1
	v_mov_b32_e32 v13, v1
	v_mov_b64_e32 v[30:31], v[14:15]
	v_mov_b64_e32 v[46:47], v[14:15]
	v_mov_b64_e32 v[62:63], v[14:15]
	v_mov_b64_e32 v[78:79], v[14:15]
	s_or_b32 s3, s13, s3
	s_mov_b32 s2, 0
	v_mov_b32_e32 v183, 0xf149f2ca
	v_mov_b32_e32 v182, 0
	v_mov_b64_e32 v[28:29], v[12:13]
	v_mov_b64_e32 v[26:27], v[10:11]
	v_mov_b64_e32 v[24:25], v[8:9]
	v_mov_b64_e32 v[22:23], v[6:7]
	v_mov_b64_e32 v[20:21], v[4:5]
	v_mov_b64_e32 v[18:19], v[2:3]
	v_mov_b64_e32 v[16:17], v[0:1]
	v_mov_b64_e32 v[44:45], v[12:13]
	v_mov_b64_e32 v[42:43], v[10:11]
	v_mov_b64_e32 v[40:41], v[8:9]
	v_mov_b64_e32 v[38:39], v[6:7]
	v_mov_b64_e32 v[36:37], v[4:5]
	v_mov_b64_e32 v[34:35], v[2:3]
	v_mov_b64_e32 v[32:33], v[0:1]
	v_mov_b64_e32 v[60:61], v[12:13]
	v_mov_b64_e32 v[58:59], v[10:11]
	v_mov_b64_e32 v[56:57], v[8:9]
	v_mov_b64_e32 v[54:55], v[6:7]
	v_mov_b64_e32 v[52:53], v[4:5]
	v_mov_b64_e32 v[50:51], v[2:3]
	v_mov_b64_e32 v[48:49], v[0:1]
	v_mov_b64_e32 v[76:77], v[12:13]
	v_mov_b64_e32 v[74:75], v[10:11]
	v_mov_b64_e32 v[72:73], v[8:9]
	v_mov_b64_e32 v[70:71], v[6:7]
	v_mov_b64_e32 v[68:69], v[4:5]
	v_mov_b64_e32 v[66:67], v[2:3]
	v_mov_b64_e32 v[64:65], v[0:1]
	s_mov_b32 s12, 0
	s_waitcnt lgkmcnt(0)
	s_barrier
	s_cmp_eq_u32 s11, 1
	s_cbranch_scc0 .Lattn_skip_b1
	s_barrier

.Lattn_pair_g0:
	v_xor_b32_e32 v225, 64, v0
	v_xor_b32_e32 v248, 0xc0, v0
	ds_read_b128 v[2:5], v6
	ds_read_b128 v[8:11], v6 offset:8704
	ds_read_b128 v[12:15], v6 offset:32
	ds_read_b128 v[226:229], v6 offset:8736
	s_waitcnt lgkmcnt(3)
	v_mfma_f32_32x32x16_bf16 v[96:111], v[2:5], v[112:115], 0
	ds_read_b128 v[2:5], v6 offset:64
	s_waitcnt lgkmcnt(3)
	v_mfma_f32_32x32x16_bf16 v[80:95], v[8:11], v[112:115], 0
	ds_read_b128 v[8:11], v6 offset:8768
	s_waitcnt lgkmcnt(3)
	v_mfma_f32_32x32x16_bf16 v[96:111], v[12:15], v[116:119], v[96:111]
	ds_read_b128 v[12:15], v6 offset:96
	s_waitcnt lgkmcnt(3)
	v_mfma_f32_32x32x16_bf16 v[80:95], v[226:229], v[116:119], v[80:95]
	ds_read_b128 v[226:229], v6 offset:8800
	s_waitcnt lgkmcnt(3)
	v_mfma_f32_32x32x16_bf16 v[96:111], v[2:5], v[120:123], v[96:111]
	ds_read_b128 v[2:5], v6 offset:17408
	s_waitcnt lgkmcnt(3)
	v_mfma_f32_32x32x16_bf16 v[80:95], v[8:11], v[120:123], v[80:95]
	ds_read_b128 v[8:11], v6 offset:26112
	s_waitcnt lgkmcnt(3)
	v_mfma_f32_32x32x16_bf16 v[96:111], v[12:15], v[124:127], v[96:111]
	ds_read_b128 v[12:15], v6 offset:17440
	s_waitcnt lgkmcnt(3)
	v_mfma_f32_32x32x16_bf16 v[80:95], v[226:229], v[124:127], v[80:95]
	ds_read_b128 v[226:229], v6 offset:26144
	s_waitcnt lgkmcnt(3)
	v_mfma_f32_32x32x16_bf16 v[184:199], v[2:5], v[112:115], 0
	ds_read_b128 v[2:5], v6 offset:17472
	s_nop 7
	v_max3_f32 v238, v96, v97, v98
	v_max3_f32 v241, v99, v100, v101
	v_max3_f32 v246, v102, v103, v104
	v_max3_f32 v247, v105, v106, v107
	v_max3_f32 v238, v238, v108, v109
	v_max3_f32 v241, v241, v110, v111
	v_max3_f32 v246, v246, v80, v81
	v_max3_f32 v247, v247, v82, v83
	s_waitcnt lgkmcnt(3)
	v_mfma_f32_32x32x16_bf16 v[200:215], v[8:11], v[112:115], 0
	ds_read_b128 v[8:11], v6 offset:26176
	v_max3_f32 v238, v238, v84, v85
	v_max3_f32 v241, v241, v86, v87
	v_max3_f32 v246, v246, v88, v89
	v_max3_f32 v247, v247, v90, v91
	v_max3_f32 v238, v238, v92, v93
	v_max3_f32 v241, v241, v94, v95
	v_max3_f32 v238, v238, v241, v246
	v_max_f32_e32 v238, v238, v247
	ds_bpermute_b32 v241, v181, v238
	s_waitcnt lgkmcnt(4)
	v_mfma_f32_32x32x16_bf16 v[184:199], v[12:15], v[116:119], v[184:199]
	ds_read_b128 v[12:15], v6 offset:17504
	s_waitcnt lgkmcnt(1)
	v_max3_f32 v7, v183, v238, v241
	v_cmp_gt_f32_e32 vcc, v7, v183
	s_cbranch_vccz .Lattn_pair_nra
	v_sub_f32_e32 v246, v183, v7
	v_mul_f32_e32 v246, 0x3e38aa3b, v246
	v_exp_f32_e32 v246, v246
	s_nop 0
	v_pk_mul_f32 v[78:79], v[78:79], v[246:247] op_sel_hi:[1,0]
	v_pk_mul_f32 v[76:77], v[76:77], v[246:247] op_sel_hi:[1,0]
	v_pk_mul_f32 v[74:75], v[74:75], v[246:247] op_sel_hi:[1,0]
	v_pk_mul_f32 v[72:73], v[72:73], v[246:247] op_sel_hi:[1,0]
	v_pk_mul_f32 v[70:71], v[70:71], v[246:247] op_sel_hi:[1,0]
	v_pk_mul_f32 v[68:69], v[68:69], v[246:247] op_sel_hi:[1,0]
	v_pk_mul_f32 v[66:67], v[66:67], v[246:247] op_sel_hi:[1,0]
	v_pk_mul_f32 v[64:65], v[64:65], v[246:247] op_sel_hi:[1,0]
	v_pk_mul_f32 v[62:63], v[62:63], v[246:247] op_sel_hi:[1,0]
	v_pk_mul_f32 v[60:61], v[60:61], v[246:247] op_sel_hi:[1,0]
	v_pk_mul_f32 v[58:59], v[58:59], v[246:247] op_sel_hi:[1,0]
	v_pk_mul_f32 v[56:57], v[56:57], v[246:247] op_sel_hi:[1,0]
	v_pk_mul_f32 v[54:55], v[54:55], v[246:247] op_sel_hi:[1,0]
	v_pk_mul_f32 v[52:53], v[52:53], v[246:247] op_sel_hi:[1,0]
	v_pk_mul_f32 v[50:51], v[50:51], v[246:247] op_sel_hi:[1,0]
	v_pk_mul_f32 v[48:49], v[48:49], v[246:247] op_sel_hi:[1,0]
	v_pk_mul_f32 v[46:47], v[46:47], v[246:247] op_sel_hi:[1,0]
	v_pk_mul_f32 v[44:45], v[44:45], v[246:247] op_sel_hi:[1,0]
	v_pk_mul_f32 v[42:43], v[42:43], v[246:247] op_sel_hi:[1,0]
	v_pk_mul_f32 v[40:41], v[40:41], v[246:247] op_sel_hi:[1,0]
	v_pk_mul_f32 v[38:39], v[38:39], v[246:247] op_sel_hi:[1,0]
	v_pk_mul_f32 v[36:37], v[36:37], v[246:247] op_sel_hi:[1,0]
	v_pk_mul_f32 v[34:35], v[34:35], v[246:247] op_sel_hi:[1,0]
	v_pk_mul_f32 v[32:33], v[32:33], v[246:247] op_sel_hi:[1,0]
	v_pk_mul_f32 v[30:31], v[30:31], v[246:247] op_sel_hi:[1,0]
	v_pk_mul_f32 v[28:29], v[28:29], v[246:247] op_sel_hi:[1,0]
	v_pk_mul_f32 v[26:27], v[26:27], v[246:247] op_sel_hi:[1,0]
	v_pk_mul_f32 v[24:25], v[24:25], v[246:247] op_sel_hi:[1,0]
	v_pk_mul_f32 v[22:23], v[22:23], v[246:247] op_sel_hi:[1,0]
	v_pk_mul_f32 v[20:21], v[20:21], v[246:247] op_sel_hi:[1,0]
	v_pk_mul_f32 v[18:19], v[18:19], v[246:247] op_sel_hi:[1,0]
	v_pk_mul_f32 v[16:17], v[16:17], v[246:247] op_sel_hi:[1,0]
	v_mul_f32_e32 v182, v182, v246
.Lattn_pair_nra:
	v_mul_f32_e32 v165, 0xbe38aa3b, v7
	s_waitcnt lgkmcnt(4)
	v_mfma_f32_32x32x16_bf16 v[200:215], v[226:229], v[116:119], v[200:215]
	ds_read_b128 v[226:229], v6 offset:26208
	v_fmamk_f32 v96, v96, 0x3e38aa3b, v165
	v_fmamk_f32 v97, v97, 0x3e38aa3b, v165
	v_fmamk_f32 v98, v98, 0x3e38aa3b, v165
	v_fmamk_f32 v99, v99, 0x3e38aa3b, v165
	v_exp_f32_e32 v96, v96
	v_exp_f32_e32 v97, v97
	v_exp_f32_e32 v98, v98
	v_exp_f32_e32 v99, v99
	v_add_f32_e32 v238, v96, v97
	v_add_f32_e32 v241, v98, v99
	v_cvt_pk_bf16_f32 v96, v96, v97
	v_cvt_pk_bf16_f32 v97, v98, v99
	s_waitcnt lgkmcnt(4)
	v_mfma_f32_32x32x16_bf16 v[184:199], v[2:5], v[120:123], v[184:199]
	v_xor_b32_e32 v6, 0x80, v0
	ds_read_b64_tr_b16 v[230:231], v0
	ds_read_b64_tr_b16 v[232:233], v0 offset:2048
	v_fmamk_f32 v100, v100, 0x3e38aa3b, v165
	v_fmamk_f32 v101, v101, 0x3e38aa3b, v165
	v_fmamk_f32 v102, v102, 0x3e38aa3b, v165
	v_fmamk_f32 v103, v103, 0x3e38aa3b, v165
	v_exp_f32_e32 v100, v100
	v_exp_f32_e32 v101, v101
	v_exp_f32_e32 v102, v102
	v_exp_f32_e32 v103, v103
	v_add_f32_e32 v246, v100, v101
	v_add_f32_e32 v247, v102, v103
	v_add_f32_e32 v238, v238, v246
	v_add_f32_e32 v241, v241, v247
	v_cvt_pk_bf16_f32 v98, v100, v101
	v_cvt_pk_bf16_f32 v99, v102, v103
	s_waitcnt lgkmcnt(5)
	v_mfma_f32_32x32x16_bf16 v[200:215], v[8:11], v[120:123], v[200:215]
	ds_read_b64_tr_b16 v[234:235], v225
	ds_read_b64_tr_b16 v[236:237], v225 offset:2048
	v_fmamk_f32 v104, v104, 0x3e38aa3b, v165
	v_fmamk_f32 v105, v105, 0x3e38aa3b, v165
	v_fmamk_f32 v106, v106, 0x3e38aa3b, v165
	v_fmamk_f32 v107, v107, 0x3e38aa3b, v165
	v_exp_f32_e32 v104, v104
	v_exp_f32_e32 v105, v105
	v_exp_f32_e32 v106, v106
	v_exp_f32_e32 v107, v107
	v_add_f32_e32 v246, v104, v105
	v_add_f32_e32 v247, v106, v107
	v_add_f32_e32 v238, v238, v246
	v_add_f32_e32 v241, v241, v247
	v_cvt_pk_bf16_f32 v104, v104, v105
	v_cvt_pk_bf16_f32 v105, v106, v107
	s_waitcnt lgkmcnt(5)
	v_mfma_f32_32x32x16_bf16 v[184:199], v[12:15], v[124:127], v[184:199]
	ds_read_b64_tr_b16 v[242:243], v6
	ds_read_b64_tr_b16 v[244:245], v6 offset:2048
	v_fmamk_f32 v108, v108, 0x3e38aa3b, v165
	v_fmamk_f32 v109, v109, 0x3e38aa3b, v165
	v_fmamk_f32 v110, v110, 0x3e38aa3b, v165
	v_fmamk_f32 v111, v111, 0x3e38aa3b, v165
	v_exp_f32_e32 v108, v108
	v_exp_f32_e32 v109, v109
	v_exp_f32_e32 v110, v110
	v_exp_f32_e32 v111, v111
	v_add_f32_e32 v246, v108, v109
	v_add_f32_e32 v247, v110, v111
	v_add_f32_e32 v238, v238, v246
	v_add_f32_e32 v241, v241, v247
	v_cvt_pk_bf16_f32 v106, v108, v109
	v_cvt_pk_bf16_f32 v107, v110, v111
	s_waitcnt lgkmcnt(6)
	v_mfma_f32_32x32x16_bf16 v[200:215], v[226:229], v[124:127], v[200:215]
	ds_read_b64_tr_b16 v[2:3], v248
	ds_read_b64_tr_b16 v[4:5], v248 offset:2048
	v_fmamk_f32 v80, v80, 0x3e38aa3b, v165
	v_fmamk_f32 v81, v81, 0x3e38aa3b, v165
	v_fmamk_f32 v82, v82, 0x3e38aa3b, v165
	v_fmamk_f32 v83, v83, 0x3e38aa3b, v165
	v_exp_f32_e32 v80, v80
	v_exp_f32_e32 v81, v81
	v_exp_f32_e32 v82, v82
	v_exp_f32_e32 v83, v83
	v_add_f32_e32 v246, v80, v81
	v_add_f32_e32 v247, v82, v83
	v_add_f32_e32 v238, v238, v246
	v_add_f32_e32 v241, v241, v247
	v_cvt_pk_bf16_f32 v80, v80, v81
	v_cvt_pk_bf16_f32 v81, v82, v83
	s_barrier
	s_waitcnt lgkmcnt(6)
	v_mfma_f32_32x32x16_bf16 v[64:79], v[230:233], v[96:99], v[64:79]
	ds_read_b64_tr_b16 v[8:9], v0 offset:4096
	ds_read_b64_tr_b16 v[10:11], v0 offset:6144
	v_fmamk_f32 v84, v84, 0x3e38aa3b, v165
	v_fmamk_f32 v85, v85, 0x3e38aa3b, v165
	v_fmamk_f32 v86, v86, 0x3e38aa3b, v165
	v_fmamk_f32 v87, v87, 0x3e38aa3b, v165
	v_exp_f32_e32 v84, v84
	v_exp_f32_e32 v85, v85
	v_exp_f32_e32 v86, v86
	v_exp_f32_e32 v87, v87
	v_add_f32_e32 v246, v84, v85
	v_add_f32_e32 v247, v86, v87
	v_add_f32_e32 v238, v238, v246
	v_add_f32_e32 v241, v241, v247
	v_cvt_pk_bf16_f32 v82, v84, v85
	v_cvt_pk_bf16_f32 v83, v86, v87
	s_waitcnt lgkmcnt(6)
	v_mfma_f32_32x32x16_bf16 v[48:63], v[234:237], v[96:99], v[48:63]
	ds_read_b64_tr_b16 v[12:13], v225 offset:4096
	ds_read_b64_tr_b16 v[14:15], v225 offset:6144
	v_fmamk_f32 v88, v88, 0x3e38aa3b, v165
	v_fmamk_f32 v89, v89, 0x3e38aa3b, v165
	v_fmamk_f32 v90, v90, 0x3e38aa3b, v165
	v_fmamk_f32 v91, v91, 0x3e38aa3b, v165
	v_exp_f32_e32 v88, v88
	v_exp_f32_e32 v89, v89
	v_exp_f32_e32 v90, v90
	v_exp_f32_e32 v91, v91
	v_add_f32_e32 v246, v88, v89
	v_add_f32_e32 v247, v90, v91
	v_add_f32_e32 v238, v238, v246
	v_add_f32_e32 v241, v241, v247
	v_cvt_pk_bf16_f32 v88, v88, v89
	v_cvt_pk_bf16_f32 v89, v90, v91
	s_waitcnt lgkmcnt(6)
	v_mfma_f32_32x32x16_bf16 v[32:47], v[242:245], v[96:99], v[32:47]
	ds_read_b64_tr_b16 v[226:227], v6 offset:4096
	ds_read_b64_tr_b16 v[228:229], v6 offset:6144
	v_fmamk_f32 v92, v92, 0x3e38aa3b, v165
	v_fmamk_f32 v93, v93, 0x3e38aa3b, v165
	v_fmamk_f32 v94, v94, 0x3e38aa3b, v165
	v_fmamk_f32 v95, v95, 0x3e38aa3b, v165
	v_exp_f32_e32 v92, v92
	v_exp_f32_e32 v93, v93
	v_exp_f32_e32 v94, v94
	v_exp_f32_e32 v95, v95
	v_add_f32_e32 v246, v92, v93
	v_add_f32_e32 v247, v94, v95
	v_add_f32_e32 v238, v238, v246
	v_add_f32_e32 v241, v241, v247
	v_cvt_pk_bf16_f32 v90, v92, v93
	v_cvt_pk_bf16_f32 v91, v94, v95
	v_add_f32_e32 v238, v238, v241
	v_add_f32_e32 v182, v182, v238
	s_waitcnt lgkmcnt(6)
	v_mfma_f32_32x32x16_bf16 v[16:31], v[2:5], v[96:99], v[16:31]
	ds_read_b64_tr_b16 v[230:231], v248 offset:4096
	ds_read_b64_tr_b16 v[232:233], v248 offset:6144
	v_max3_f32 v238, v184, v185, v186
	v_max3_f32 v241, v187, v188, v189
	v_max3_f32 v246, v190, v191, v192
	v_max3_f32 v247, v193, v194, v195
	v_max3_f32 v238, v238, v196, v197
	v_max3_f32 v241, v241, v198, v199
	v_max3_f32 v246, v246, v200, v201
	v_max3_f32 v247, v247, v202, v203
	s_waitcnt lgkmcnt(6)
	v_mfma_f32_32x32x16_bf16 v[64:79], v[8:11], v[104:107], v[64:79]
	ds_read_b64_tr_b16 v[234:235], v0 offset:8192
	ds_read_b64_tr_b16 v[236:237], v0 offset:10240
	v_max3_f32 v238, v238, v204, v205
	v_max3_f32 v241, v241, v206, v207
	v_max3_f32 v246, v246, v208, v209
	v_max3_f32 v247, v247, v210, v211
	v_max3_f32 v238, v238, v212, v213
	v_max3_f32 v241, v241, v214, v215
	v_max3_f32 v238, v238, v241, v246
	v_max_f32_e32 v238, v238, v247
	ds_bpermute_b32 v241, v181, v238
	s_waitcnt lgkmcnt(7)
	v_mfma_f32_32x32x16_bf16 v[48:63], v[12:15], v[104:107], v[48:63]
	ds_read_b64_tr_b16 v[242:243], v225 offset:8192
	ds_read_b64_tr_b16 v[244:245], v225 offset:10240
	s_waitcnt lgkmcnt(7)
	v_mfma_f32_32x32x16_bf16 v[32:47], v[226:229], v[104:107], v[32:47]
	ds_read_b64_tr_b16 v[2:3], v6 offset:8192
	ds_read_b64_tr_b16 v[4:5], v6 offset:10240
	s_waitcnt lgkmcnt(4)
	v_max3_f32 v183, v7, v238, v241
	v_mul_f32_e32 v165, 0xbe38aa3b, v183
	s_waitcnt lgkmcnt(7)
	v_mfma_f32_32x32x16_bf16 v[16:31], v[230:233], v[104:107], v[16:31]
	ds_read_b64_tr_b16 v[8:9], v248 offset:8192
	ds_read_b64_tr_b16 v[10:11], v248 offset:10240
	v_fmamk_f32 v184, v184, 0x3e38aa3b, v165
	v_fmamk_f32 v185, v185, 0x3e38aa3b, v165
	v_fmamk_f32 v186, v186, 0x3e38aa3b, v165
	v_fmamk_f32 v187, v187, 0x3e38aa3b, v165
	v_exp_f32_e32 v184, v184
	v_exp_f32_e32 v185, v185
	s_waitcnt lgkmcnt(7)
	v_mfma_f32_32x32x16_bf16 v[64:79], v[234:237], v[80:83], v[64:79]
	ds_read_b64_tr_b16 v[12:13], v0 offset:12288
	ds_read_b64_tr_b16 v[14:15], v0 offset:14336
	v_exp_f32_e32 v186, v186
	v_exp_f32_e32 v187, v187
	v_cvt_pk_bf16_f32 v100, v184, v185
	s_nop 0
	v_cvt_pk_bf16_f32 v101, v186, v187
	s_waitcnt lgkmcnt(6)
	v_mfma_f32_32x32x16_bf16 v[48:63], v[242:245], v[80:83], v[48:63]
	ds_read_b64_tr_b16 v[226:227], v225 offset:12288
	ds_read_b64_tr_b16 v[228:229], v225 offset:14336
	v_fmamk_f32 v188, v188, 0x3e38aa3b, v165
	v_fmamk_f32 v189, v189, 0x3e38aa3b, v165
	v_fmamk_f32 v190, v190, 0x3e38aa3b, v165
	v_fmamk_f32 v191, v191, 0x3e38aa3b, v165
	v_exp_f32_e32 v188, v188
	v_exp_f32_e32 v189, v189
	s_waitcnt lgkmcnt(6)
	v_mfma_f32_32x32x16_bf16 v[32:47], v[2:5], v[80:83], v[32:47]
	ds_read_b64_tr_b16 v[230:231], v6 offset:12288
	ds_read_b64_tr_b16 v[232:233], v6 offset:14336
	v_exp_f32_e32 v190, v190
	v_exp_f32_e32 v191, v191
	v_cvt_pk_bf16_f32 v102, v188, v189
	s_nop 0
	v_cvt_pk_bf16_f32 v103, v190, v191
	s_waitcnt lgkmcnt(6)
	v_mfma_f32_32x32x16_bf16 v[16:31], v[8:11], v[80:83], v[16:31]
	ds_read_b64_tr_b16 v[234:235], v248 offset:12288
	ds_read_b64_tr_b16 v[236:237], v248 offset:14336
	v_fmamk_f32 v192, v192, 0x3e38aa3b, v165
	v_fmamk_f32 v193, v193, 0x3e38aa3b, v165
	v_fmamk_f32 v194, v194, 0x3e38aa3b, v165
	v_fmamk_f32 v195, v195, 0x3e38aa3b, v165
	v_exp_f32_e32 v192, v192
	v_exp_f32_e32 v193, v193
	s_waitcnt lgkmcnt(6)
	v_mfma_f32_32x32x16_bf16 v[64:79], v[12:15], v[88:91], v[64:79]
	ds_read_b64_tr_b16 v[242:243], v0 offset:16384
	ds_read_b64_tr_b16 v[244:245], v0 offset:18432
	v_exp_f32_e32 v194, v194
	v_exp_f32_e32 v195, v195
	v_cvt_pk_bf16_f32 v108, v192, v193
	s_nop 0
	v_cvt_pk_bf16_f32 v109, v194, v195
	s_waitcnt lgkmcnt(6)
	v_mfma_f32_32x32x16_bf16 v[48:63], v[226:229], v[88:91], v[48:63]
	ds_read_b64_tr_b16 v[2:3], v225 offset:16384
	ds_read_b64_tr_b16 v[4:5], v225 offset:18432
	v_fmamk_f32 v196, v196, 0x3e38aa3b, v165
	v_fmamk_f32 v197, v197, 0x3e38aa3b, v165
	v_fmamk_f32 v198, v198, 0x3e38aa3b, v165
	v_fmamk_f32 v199, v199, 0x3e38aa3b, v165
	v_exp_f32_e32 v196, v196
	v_exp_f32_e32 v197, v197
	s_waitcnt lgkmcnt(6)
	v_mfma_f32_32x32x16_bf16 v[32:47], v[230:233], v[88:91], v[32:47]
	ds_read_b64_tr_b16 v[8:9], v6 offset:16384
	ds_read_b64_tr_b16 v[10:11], v6 offset:18432
	v_exp_f32_e32 v198, v198
	v_exp_f32_e32 v199, v199
	v_cvt_pk_bf16_f32 v110, v196, v197
	s_nop 0
	v_cvt_pk_bf16_f32 v111, v198, v199
	s_waitcnt lgkmcnt(6)
	v_mfma_f32_32x32x16_bf16 v[16:31], v[234:237], v[88:91], v[16:31]
	ds_read_b64_tr_b16 v[12:13], v248 offset:16384
	ds_read_b64_tr_b16 v[14:15], v248 offset:18432
	v_cmp_gt_f32_e32 vcc, v183, v7
	s_cbranch_vccz .Lattn_pair_nrb
	s_nop 15
	v_sub_f32_e32 v246, v7, v183
	v_mul_f32_e32 v246, 0x3e38aa3b, v246
	v_exp_f32_e32 v246, v246
	s_nop 0
	v_pk_mul_f32 v[78:79], v[78:79], v[246:247] op_sel_hi:[1,0]
	v_pk_mul_f32 v[76:77], v[76:77], v[246:247] op_sel_hi:[1,0]
	v_pk_mul_f32 v[74:75], v[74:75], v[246:247] op_sel_hi:[1,0]
	v_pk_mul_f32 v[72:73], v[72:73], v[246:247] op_sel_hi:[1,0]
	v_pk_mul_f32 v[70:71], v[70:71], v[246:247] op_sel_hi:[1,0]
	v_pk_mul_f32 v[68:69], v[68:69], v[246:247] op_sel_hi:[1,0]
	v_pk_mul_f32 v[66:67], v[66:67], v[246:247] op_sel_hi:[1,0]
	v_pk_mul_f32 v[64:65], v[64:65], v[246:247] op_sel_hi:[1,0]
	v_pk_mul_f32 v[62:63], v[62:63], v[246:247] op_sel_hi:[1,0]
	v_pk_mul_f32 v[60:61], v[60:61], v[246:247] op_sel_hi:[1,0]
	v_pk_mul_f32 v[58:59], v[58:59], v[246:247] op_sel_hi:[1,0]
	v_pk_mul_f32 v[56:57], v[56:57], v[246:247] op_sel_hi:[1,0]
	v_pk_mul_f32 v[54:55], v[54:55], v[246:247] op_sel_hi:[1,0]
	v_pk_mul_f32 v[52:53], v[52:53], v[246:247] op_sel_hi:[1,0]
	v_pk_mul_f32 v[50:51], v[50:51], v[246:247] op_sel_hi:[1,0]
	v_pk_mul_f32 v[48:49], v[48:49], v[246:247] op_sel_hi:[1,0]
	v_pk_mul_f32 v[46:47], v[46:47], v[246:247] op_sel_hi:[1,0]
	v_pk_mul_f32 v[44:45], v[44:45], v[246:247] op_sel_hi:[1,0]
	v_pk_mul_f32 v[42:43], v[42:43], v[246:247] op_sel_hi:[1,0]
	v_pk_mul_f32 v[40:41], v[40:41], v[246:247] op_sel_hi:[1,0]
	v_pk_mul_f32 v[38:39], v[38:39], v[246:247] op_sel_hi:[1,0]
	v_pk_mul_f32 v[36:37], v[36:37], v[246:247] op_sel_hi:[1,0]
	v_pk_mul_f32 v[34:35], v[34:35], v[246:247] op_sel_hi:[1,0]
	v_pk_mul_f32 v[32:33], v[32:33], v[246:247] op_sel_hi:[1,0]
	v_pk_mul_f32 v[30:31], v[30:31], v[246:247] op_sel_hi:[1,0]
	v_pk_mul_f32 v[28:29], v[28:29], v[246:247] op_sel_hi:[1,0]
	v_pk_mul_f32 v[26:27], v[26:27], v[246:247] op_sel_hi:[1,0]
	v_pk_mul_f32 v[24:25], v[24:25], v[246:247] op_sel_hi:[1,0]
	v_pk_mul_f32 v[22:23], v[22:23], v[246:247] op_sel_hi:[1,0]
	v_pk_mul_f32 v[20:21], v[20:21], v[246:247] op_sel_hi:[1,0]
	v_pk_mul_f32 v[18:19], v[18:19], v[246:247] op_sel_hi:[1,0]
	v_pk_mul_f32 v[16:17], v[16:17], v[246:247] op_sel_hi:[1,0]
	v_mul_f32_e32 v182, v182, v246
.Lattn_pair_nrb:
	s_cmp_eq_u32 s11, 0
	s_cbranch_scc0 .Lattn_pair_b6plain
	s_add_i32 s14, s12, 2
	s_cmp_gt_u32 s14, s10
	s_cbranch_scc1 .Lattn_pair_b6plain
	s_and_b32 s14, s13, 1
	s_mul_i32 s15, s14, 0x8800
	s_mul_i32 s14, s14, 0x9000
	v_add3_u32 v246, v176, s15, v174
	v_add3_u32 v247, v177, s14, v175
	s_waitcnt lgkmcnt(6)
	v_mfma_f32_32x32x16_bf16 v[64:79], v[242:245], v[100:103], v[64:79]
	ds_read_b64_tr_b16 v[226:227], v0 offset:20480
	ds_read_b64_tr_b16 v[228:229], v0 offset:22528
	v_fmamk_f32 v200, v200, 0x3e38aa3b, v165
	v_fmamk_f32 v201, v201, 0x3e38aa3b, v165
	v_fmamk_f32 v202, v202, 0x3e38aa3b, v165
	v_fmamk_f32 v203, v203, 0x3e38aa3b, v165
	v_exp_f32_e32 v200, v200
	v_exp_f32_e32 v201, v201
	s_waitcnt vmcnt(7)
	ds_write_b128 v246, v[128:131]
	s_waitcnt lgkmcnt(7)
	v_mfma_f32_32x32x16_bf16 v[48:63], v[2:5], v[100:103], v[48:63]
	ds_read_b64_tr_b16 v[230:231], v225 offset:20480
	ds_read_b64_tr_b16 v[232:233], v225 offset:22528
	v_exp_f32_e32 v202, v202
	v_exp_f32_e32 v203, v203
	v_cvt_pk_bf16_f32 v84, v200, v201
	s_nop 0
	v_cvt_pk_bf16_f32 v85, v202, v203
	s_waitcnt vmcnt(6)
	ds_write_b128 v247, v[132:135]
	s_waitcnt lgkmcnt(8)
	v_mfma_f32_32x32x16_bf16 v[32:47], v[8:11], v[100:103], v[32:47]
	ds_read_b64_tr_b16 v[234:235], v6 offset:20480
	ds_read_b64_tr_b16 v[236:237], v6 offset:22528
	v_fmamk_f32 v204, v204, 0x3e38aa3b, v165
	v_fmamk_f32 v205, v205, 0x3e38aa3b, v165
	v_fmamk_f32 v206, v206, 0x3e38aa3b, v165
	v_fmamk_f32 v207, v207, 0x3e38aa3b, v165
	v_exp_f32_e32 v204, v204
	v_exp_f32_e32 v205, v205
	s_waitcnt vmcnt(5)
	ds_write_b128 v246, v[136:139] offset:8704
	s_waitcnt lgkmcnt(9)
	v_mfma_f32_32x32x16_bf16 v[16:31], v[12:15], v[100:103], v[16:31]
	ds_read_b64_tr_b16 v[242:243], v248 offset:20480
	ds_read_b64_tr_b16 v[244:245], v248 offset:22528
	v_exp_f32_e32 v206, v206
	v_exp_f32_e32 v207, v207
	v_cvt_pk_bf16_f32 v86, v204, v205
	s_nop 0
	v_cvt_pk_bf16_f32 v87, v206, v207
	s_waitcnt vmcnt(4)
	ds_write_b128 v247, v[140:143] offset:8192
	s_waitcnt lgkmcnt(10)
	v_mfma_f32_32x32x16_bf16 v[64:79], v[226:229], v[108:111], v[64:79]
	ds_read_b64_tr_b16 v[2:3], v0 offset:24576
	ds_read_b64_tr_b16 v[4:5], v0 offset:26624
	v_fmamk_f32 v208, v208, 0x3e38aa3b, v165
	v_fmamk_f32 v209, v209, 0x3e38aa3b, v165
	v_fmamk_f32 v210, v210, 0x3e38aa3b, v165
	v_fmamk_f32 v211, v211, 0x3e38aa3b, v165
	v_exp_f32_e32 v208, v208
	v_exp_f32_e32 v209, v209
	s_waitcnt vmcnt(3)
	ds_write_b128 v246, v[144:147] offset:17408
	s_waitcnt lgkmcnt(10)
	v_mfma_f32_32x32x16_bf16 v[48:63], v[230:233], v[108:111], v[48:63]
	ds_read_b64_tr_b16 v[8:9], v225 offset:24576
	ds_read_b64_tr_b16 v[10:11], v225 offset:26624
	v_exp_f32_e32 v210, v210
	v_exp_f32_e32 v211, v211
	v_cvt_pk_bf16_f32 v92, v208, v209
	s_nop 0
	v_cvt_pk_bf16_f32 v93, v210, v211
	s_waitcnt vmcnt(2)
	ds_write_b128 v247, v[148:151] offset:16384
	s_waitcnt lgkmcnt(10)
	v_mfma_f32_32x32x16_bf16 v[32:47], v[234:237], v[108:111], v[32:47]
	ds_read_b64_tr_b16 v[12:13], v6 offset:24576
	ds_read_b64_tr_b16 v[14:15], v6 offset:26624
	v_fmamk_f32 v212, v212, 0x3e38aa3b, v165
	v_fmamk_f32 v213, v213, 0x3e38aa3b, v165
	v_fmamk_f32 v214, v214, 0x3e38aa3b, v165
	v_fmamk_f32 v215, v215, 0x3e38aa3b, v165
	v_exp_f32_e32 v212, v212
	v_exp_f32_e32 v213, v213
	s_waitcnt vmcnt(1)
	ds_write_b128 v246, v[152:155] offset:26112
	s_waitcnt lgkmcnt(10)
	v_mfma_f32_32x32x16_bf16 v[16:31], v[242:245], v[108:111], v[16:31]
	ds_read_b64_tr_b16 v[226:227], v248 offset:24576
	ds_read_b64_tr_b16 v[228:229], v248 offset:26624
	v_exp_f32_e32 v214, v214
	v_exp_f32_e32 v215, v215
	v_cvt_pk_bf16_f32 v94, v212, v213
	s_nop 0
	v_cvt_pk_bf16_f32 v95, v214, v215
	s_waitcnt vmcnt(0)
	ds_write_b128 v247, v[156:159] offset:24576
	s_waitcnt lgkmcnt(10)
	v_mfma_f32_32x32x16_bf16 v[64:79], v[2:5], v[84:87], v[64:79]
	ds_read_b64_tr_b16 v[230:231], v0 offset:28672
	ds_read_b64_tr_b16 v[232:233], v0 offset:30720
	v_add_f32_e32 v238, v184, v185
	v_add_f32_e32 v241, v186, v187
	v_add_f32_e32 v238, v238, v188
	v_add_f32_e32 v241, v241, v189
	v_lshlrev_b32_e32 v96, 1, v173
	v_add_u32_e32 v80, 0xffffffa0, v164
	v_ashrrev_i32_e32 v81, 31, v80
	v_lshlrev_b64 v[82:83], 11, v[80:81]
	v_or_b32_e32 v82, v82, v96
	s_waitcnt lgkmcnt(9)
	v_mfma_f32_32x32x16_bf16 v[48:63], v[8:11], v[84:87], v[48:63]
	ds_read_b64_tr_b16 v[234:235], v225 offset:28672
	ds_read_b64_tr_b16 v[236:237], v225 offset:30720
	v_add_f32_e32 v238, v238, v190
	v_add_f32_e32 v241, v241, v191
	v_add_f32_e32 v238, v238, v192
	v_add_f32_e32 v241, v241, v193
	v_lshl_add_u64 v[88:89], s[86:87], 0, v[82:83]
	v_lshl_add_u64 v[90:91], s[88:89], 0, v[82:83]
	global_load_dwordx4 v[128:131], v[88:89], off
	global_load_dwordx4 v[132:135], v[90:91], off
	s_waitcnt lgkmcnt(8)
	v_mfma_f32_32x32x16_bf16 v[32:47], v[12:15], v[84:87], v[32:47]
	ds_read_b64_tr_b16 v[242:243], v6 offset:28672
	ds_read_b64_tr_b16 v[244:245], v6 offset:30720
	v_add_f32_e32 v238, v238, v194
	v_add_f32_e32 v241, v241, v195
	v_add_f32_e32 v238, v238, v196
	v_add_f32_e32 v241, v241, v197
	v_subrev_u32_e32 v80, 64, v164
	v_ashrrev_i32_e32 v81, 31, v80
	v_lshlrev_b64 v[82:83], 11, v[80:81]
	v_or_b32_e32 v82, v82, v96
	s_waitcnt lgkmcnt(7)
	v_mfma_f32_32x32x16_bf16 v[16:31], v[226:229], v[84:87], v[16:31]
	ds_read_b64_tr_b16 v[2:3], v248 offset:28672
	ds_read_b64_tr_b16 v[4:5], v248 offset:30720
	v_add_f32_e32 v238, v238, v198
	v_add_f32_e32 v241, v241, v199
	v_add_f32_e32 v238, v238, v200
	v_add_f32_e32 v241, v241, v201
	v_lshl_add_u64 v[88:89], s[86:87], 0, v[82:83]
	v_lshl_add_u64 v[90:91], s[88:89], 0, v[82:83]
	global_load_dwordx4 v[136:139], v[88:89], off
	global_load_dwordx4 v[140:143], v[90:91], off
	s_waitcnt lgkmcnt(6)
	v_mfma_f32_32x32x16_bf16 v[64:79], v[230:233], v[92:95], v[64:79]
	v_add_f32_e32 v238, v238, v202
	v_add_f32_e32 v241, v241, v203
	v_add_f32_e32 v238, v238, v204
	v_add_f32_e32 v241, v241, v205
	v_subrev_u32_e32 v80, 32, v164
	v_ashrrev_i32_e32 v81, 31, v80
	v_lshlrev_b64 v[82:83], 11, v[80:81]
	v_or_b32_e32 v82, v82, v96
	s_waitcnt lgkmcnt(4)
	v_mfma_f32_32x32x16_bf16 v[48:63], v[234:237], v[92:95], v[48:63]
	v_add_f32_e32 v238, v238, v206
	v_add_f32_e32 v241, v241, v207
	v_add_f32_e32 v238, v238, v208
	v_add_f32_e32 v241, v241, v209
	v_lshl_add_u64 v[88:89], s[86:87], 0, v[82:83]
	v_lshl_add_u64 v[90:91], s[88:89], 0, v[82:83]
	global_load_dwordx4 v[144:147], v[88:89], off
	global_load_dwordx4 v[148:151], v[90:91], off
	s_waitcnt lgkmcnt(2)
	v_mfma_f32_32x32x16_bf16 v[32:47], v[242:245], v[92:95], v[32:47]
	v_add_f32_e32 v238, v238, v210
	v_add_f32_e32 v241, v241, v211
	v_add_f32_e32 v238, v238, v212
	v_add_f32_e32 v241, v241, v213
	v_ashrrev_i32_e32 v165, 31, v164
	v_lshlrev_b64 v[82:83], 11, v[164:165]
	v_or_b32_e32 v82, v82, v96
	v_lshl_add_u64 v[88:89], s[86:87], 0, v[82:83]
	s_waitcnt lgkmcnt(0)
	v_mfma_f32_32x32x16_bf16 v[16:31], v[2:5], v[92:95], v[16:31]
	v_add_f32_e32 v238, v238, v214
	v_add_f32_e32 v241, v241, v215
	v_add_f32_e32 v238, v238, v241
	v_add_f32_e32 v182, v182, v238
	v_lshl_add_u64 v[90:91], s[88:89], 0, v[82:83]
	global_load_dwordx4 v[152:155], v[88:89], off
	global_load_dwordx4 v[156:159], v[90:91], off
	s_branch .Lattn_stg_done
.Lattn_pair_b6plain:
	s_waitcnt lgkmcnt(6)
	v_mfma_f32_32x32x16_bf16 v[64:79], v[242:245], v[100:103], v[64:79]
	ds_read_b64_tr_b16 v[226:227], v0 offset:20480
	ds_read_b64_tr_b16 v[228:229], v0 offset:22528
	v_fmamk_f32 v200, v200, 0x3e38aa3b, v165
	v_fmamk_f32 v201, v201, 0x3e38aa3b, v165
	v_fmamk_f32 v202, v202, 0x3e38aa3b, v165
	v_fmamk_f32 v203, v203, 0x3e38aa3b, v165
	v_exp_f32_e32 v200, v200
	v_exp_f32_e32 v201, v201
	s_waitcnt lgkmcnt(6)
	v_mfma_f32_32x32x16_bf16 v[48:63], v[2:5], v[100:103], v[48:63]
	ds_read_b64_tr_b16 v[230:231], v225 offset:20480
	ds_read_b64_tr_b16 v[232:233], v225 offset:22528
	v_exp_f32_e32 v202, v202
	v_exp_f32_e32 v203, v203
	v_cvt_pk_bf16_f32 v84, v200, v201
	s_nop 0
	v_cvt_pk_bf16_f32 v85, v202, v203
	s_waitcnt lgkmcnt(6)
	v_mfma_f32_32x32x16_bf16 v[32:47], v[8:11], v[100:103], v[32:47]
	ds_read_b64_tr_b16 v[234:235], v6 offset:20480
	ds_read_b64_tr_b16 v[236:237], v6 offset:22528
	v_fmamk_f32 v204, v204, 0x3e38aa3b, v165
	v_fmamk_f32 v205, v205, 0x3e38aa3b, v165
	v_fmamk_f32 v206, v206, 0x3e38aa3b, v165
	v_fmamk_f32 v207, v207, 0x3e38aa3b, v165
	v_exp_f32_e32 v204, v204
	v_exp_f32_e32 v205, v205
	s_waitcnt lgkmcnt(6)
	v_mfma_f32_32x32x16_bf16 v[16:31], v[12:15], v[100:103], v[16:31]
	ds_read_b64_tr_b16 v[242:243], v248 offset:20480
	ds_read_b64_tr_b16 v[244:245], v248 offset:22528
	v_exp_f32_e32 v206, v206
	v_exp_f32_e32 v207, v207
	v_cvt_pk_bf16_f32 v86, v204, v205
	s_nop 0
	v_cvt_pk_bf16_f32 v87, v206, v207
	s_waitcnt lgkmcnt(6)
	v_mfma_f32_32x32x16_bf16 v[64:79], v[226:229], v[108:111], v[64:79]
	ds_read_b64_tr_b16 v[2:3], v0 offset:24576
	ds_read_b64_tr_b16 v[4:5], v0 offset:26624
	v_fmamk_f32 v208, v208, 0x3e38aa3b, v165
	v_fmamk_f32 v209, v209, 0x3e38aa3b, v165
	v_fmamk_f32 v210, v210, 0x3e38aa3b, v165
	v_fmamk_f32 v211, v211, 0x3e38aa3b, v165
	v_exp_f32_e32 v208, v208
	v_exp_f32_e32 v209, v209
	s_waitcnt lgkmcnt(6)
	v_mfma_f32_32x32x16_bf16 v[48:63], v[230:233], v[108:111], v[48:63]
	ds_read_b64_tr_b16 v[8:9], v225 offset:24576
	ds_read_b64_tr_b16 v[10:11], v225 offset:26624
	v_exp_f32_e32 v210, v210
	v_exp_f32_e32 v211, v211
	v_cvt_pk_bf16_f32 v92, v208, v209
	s_nop 0
	v_cvt_pk_bf16_f32 v93, v210, v211
	s_waitcnt lgkmcnt(6)
	v_mfma_f32_32x32x16_bf16 v[32:47], v[234:237], v[108:111], v[32:47]
	ds_read_b64_tr_b16 v[12:13], v6 offset:24576
	ds_read_b64_tr_b16 v[14:15], v6 offset:26624
	v_fmamk_f32 v212, v212, 0x3e38aa3b, v165
	v_fmamk_f32 v213, v213, 0x3e38aa3b, v165
	v_fmamk_f32 v214, v214, 0x3e38aa3b, v165
	v_fmamk_f32 v215, v215, 0x3e38aa3b, v165
	v_exp_f32_e32 v212, v212
	v_exp_f32_e32 v213, v213
	s_waitcnt lgkmcnt(6)
	v_mfma_f32_32x32x16_bf16 v[16:31], v[242:245], v[108:111], v[16:31]
	ds_read_b64_tr_b16 v[226:227], v248 offset:24576
	ds_read_b64_tr_b16 v[228:229], v248 offset:26624
	v_exp_f32_e32 v214, v214
	v_exp_f32_e32 v215, v215
	v_cvt_pk_bf16_f32 v94, v212, v213
	s_nop 0
	v_cvt_pk_bf16_f32 v95, v214, v215
	s_waitcnt lgkmcnt(6)
	v_mfma_f32_32x32x16_bf16 v[64:79], v[2:5], v[84:87], v[64:79]
	ds_read_b64_tr_b16 v[230:231], v0 offset:28672
	ds_read_b64_tr_b16 v[232:233], v0 offset:30720
	v_add_f32_e32 v238, v184, v185
	v_add_f32_e32 v241, v186, v187
	v_add_f32_e32 v238, v238, v188
	v_add_f32_e32 v241, v241, v189
	s_waitcnt lgkmcnt(6)
	v_mfma_f32_32x32x16_bf16 v[48:63], v[8:11], v[84:87], v[48:63]
	ds_read_b64_tr_b16 v[234:235], v225 offset:28672
	ds_read_b64_tr_b16 v[236:237], v225 offset:30720
	v_add_f32_e32 v238, v238, v190
	v_add_f32_e32 v241, v241, v191
	v_add_f32_e32 v238, v238, v192
	v_add_f32_e32 v241, v241, v193
	s_waitcnt lgkmcnt(6)
	v_mfma_f32_32x32x16_bf16 v[32:47], v[12:15], v[84:87], v[32:47]
	ds_read_b64_tr_b16 v[242:243], v6 offset:28672
	ds_read_b64_tr_b16 v[244:245], v6 offset:30720
	v_add_f32_e32 v238, v238, v194
	v_add_f32_e32 v241, v241, v195
	v_add_f32_e32 v238, v238, v196
	v_add_f32_e32 v241, v241, v197
	s_waitcnt lgkmcnt(6)
	v_mfma_f32_32x32x16_bf16 v[16:31], v[226:229], v[84:87], v[16:31]
	ds_read_b64_tr_b16 v[2:3], v248 offset:28672
	ds_read_b64_tr_b16 v[4:5], v248 offset:30720
	v_add_f32_e32 v238, v238, v198
	v_add_f32_e32 v241, v241, v199
	v_add_f32_e32 v238, v238, v200
	v_add_f32_e32 v241, v241, v201
	s_waitcnt lgkmcnt(6)
	v_mfma_f32_32x32x16_bf16 v[64:79], v[230:233], v[92:95], v[64:79]
	v_add_f32_e32 v238, v238, v202
	v_add_f32_e32 v241, v241, v203
	v_add_f32_e32 v238, v238, v204
	v_add_f32_e32 v241, v241, v205
	s_waitcnt lgkmcnt(4)
	v_mfma_f32_32x32x16_bf16 v[48:63], v[234:237], v[92:95], v[48:63]
	v_add_f32_e32 v238, v238, v206
	v_add_f32_e32 v241, v241, v207
	v_add_f32_e32 v238, v238, v208
	v_add_f32_e32 v241, v241, v209
	s_waitcnt lgkmcnt(2)
	v_mfma_f32_32x32x16_bf16 v[32:47], v[242:245], v[92:95], v[32:47]
	v_add_f32_e32 v238, v238, v210
	v_add_f32_e32 v241, v241, v211
	v_add_f32_e32 v238, v238, v212
	v_add_f32_e32 v241, v241, v213
	s_waitcnt lgkmcnt(0)
	v_mfma_f32_32x32x16_bf16 v[16:31], v[2:5], v[92:95], v[16:31]
	v_add_f32_e32 v238, v238, v214
	v_add_f32_e32 v241, v241, v215
	v_add_f32_e32 v238, v238, v241
	v_add_f32_e32 v182, v182, v238
	s_branch .LBB0_125
